# SwiGLU epilogue: log2(e) folded into the per-row RMS scales (gate*rs*log2e, up*rs*ln2, exp2 of the negated scaled gate), one f32 multiply less per output
# speedup vs baseline: 1.0036x; 1.0025x over previous
; __device__ __forceinline__ unsigned cvtpk(float lo, float hi) { f32x2 v = {lo, hi}; bf16x2_t b = __builtin_convertvector(v, bf16x2_t); return __builtin_bit_cast(unsigned, b); }
; __device__ __forceinline__ float silu_f(float x) { return x * __builtin_amdgcn_rcpf(1.0f + __builtin_amdgcn_exp2f(-LOG2E * x)); }
;     __device__ __forceinline__ void operator()(const pg8::f32x4 (&acc)[2][2][4][2], const pg8::Unit& u, int wr, int wc, int fr, int fq) const {
;     ...
;         if (kind == EK_ACT) {
;             float rsv[2][4];
; #pragma unroll
;             for (int ai = 0; ai < 2; ++ai)
; #pragma unroll
;                 for (int m = 0; m < 4; ++m) rsv[ai][m] = fin[rowb + 128 * ai + 16 * m];
; #pragma unroll
;             for (int ai = 0; ai < 2; ++ai)
; #pragma unroll
;                 for (int m = 0; m < 4; ++m) {
;                     bf16_t* rp = o0 + (size_t)(rowb + 128 * ai + 16 * m) * ldc + u.pn * 128 + wc * 32 + (PERM ? 8 : 4) * fq;
;                     const float rs = __builtin_amdgcn_rsqf(rsv[ai][m] * (1.0f / DM) + EPS);
;                     u32x2 wn[2];
; #pragma unroll
;                     for (int n = 0; n < 2; ++n) {
;                         const pg8::f32x4 g = acc[ai][0][m][n] * rs, up = acc[ai][1][m][n] * rs;
;                         wn[n].x = cvtpk(silu_f(g[0]) * up[0], silu_f(g[1]) * up[1]); wn[n].y = cvtpk(silu_f(g[2]) * up[2], silu_f(g[3]) * up[3]);
;                     }
;                     if (PERM) { *(u32x4*)rp = (u32x4){wn[0].x, wn[0].y, wn[1].x, wn[1].y}; }
;                     else { *(u32x2*)rp = wn[0]; *(u32x2*)(rp + 16) = wn[1]; }
;                 }
.LBB0_1240:
	v_ashrrev_i32_e32 v229, 31, v228
	v_lshl_add_u64 v[66:67], v[228:229], 2, v[136:137]
	global_load_dword v64, v[66:67], off
	global_load_dword v149, v[66:67], off offset:64
	global_load_dword v146, v[66:67], off offset:128
	global_load_dword v144, v[66:67], off offset:192
	global_load_dword v142, v[66:67], off offset:512
	global_load_dword v140, v[66:67], off offset:576
	global_load_dword v138, v[66:67], off offset:640
	global_load_dword v136, v[66:67], off offset:704
	v_mad_i64_i32 v[66:67], s[8:9], v65, v228, 0
	s_lshl_b32 s8, s54, 7
	s_ashr_i32 s9, s8, 31
	v_lshl_add_u64 v[66:67], v[66:67], 1, v[68:69]
	s_lshl_b64 s[8:9], s[8:9], 1
	v_readlane_b32 s10, v253, 13
	v_lshl_add_u64 v[66:67], v[66:67], 0, s[8:9]
	s_lshl_b32 s80, s10, 1
	v_lshl_add_u64 v[66:67], v[66:67], 0, s[80:81]
	v_or_b32_e32 v148, 16, v228
	v_lshl_add_u64 v[66:67], v[66:67], 0, v[214:215]
	v_or_b32_e32 v147, 32, v228
	v_or_b32_e32 v145, 48, v228
	v_add_u32_e32 v143, 0x80, v228
	v_add_u32_e32 v141, 0x90, v228
	v_add_u32_e32 v139, 0xa0, v228
	v_add_u32_e32 v137, 0xb0, v228
	s_waitcnt vmcnt(7)
	v_fmamk_f32 v64, v64, 0x3a800000, v244
	v_rsq_f32_e32 v64, v64
	s_nop 0
	v_mul_f32_e32 v192, 0x3fb8aa3b, v64
	v_mul_f32_e32 v194, 0x3f317218, v64
	v_pk_mul_f32 v[132:133], v[132:133], v[192:193] op_sel_hi:[1,0]
	v_pk_mul_f32 v[70:71], v[134:135], v[192:193] op_sel_hi:[1,0]
	v_exp_f32_e64 v134, -v132
	v_exp_f32_e64 v135, -v133
	v_pk_mul_f32 v[124:125], v[124:125], v[194:195] op_sel_hi:[1,0]
	v_pk_mul_f32 v[126:127], v[126:127], v[194:195] op_sel_hi:[1,0]
	v_add_f32_e32 v134, 1.0, v134
	v_add_f32_e32 v135, 1.0, v135
	v_rcp_f32_e32 v134, v134
	v_rcp_f32_e32 v135, v135
	v_pk_mul_f32 v[122:123], v[122:123], v[194:195] op_sel_hi:[1,0]
	v_pk_mul_f32 v[120:121], v[120:121], v[194:195] op_sel_hi:[1,0]
	v_pk_mul_f32 v[132:133], v[132:133], v[134:135]
	s_nop 0
	v_pk_mul_f32 v[124:125], v[124:125], v[132:133]
	s_nop 0
	v_cvt_pk_bf16_f32 v124, v124, v125
	v_exp_f32_e64 v125, -v70
	s_nop 0
	v_add_f32_e32 v125, 1.0, v125
	v_rcp_f32_e32 v132, v125
	v_exp_f32_e64 v125, -v71
	s_nop 0
	v_add_f32_e32 v125, 1.0, v125
	v_rcp_f32_e32 v133, v125
	s_nop 0
	v_pk_mul_f32 v[70:71], v[70:71], v[132:133]
	s_nop 0
	v_pk_mul_f32 v[70:71], v[126:127], v[70:71]
	v_pk_mul_f32 v[126:127], v[128:129], v[192:193] op_sel_hi:[1,0]
	v_cvt_pk_bf16_f32 v125, v70, v71
	v_pk_mul_f32 v[70:71], v[130:131], v[192:193] op_sel_hi:[1,0]
	v_exp_f32_e64 v64, -v126
	s_nop 0
	v_add_f32_e32 v64, 1.0, v64
	v_rcp_f32_e32 v128, v64
	v_exp_f32_e64 v64, -v127
	s_nop 0
	v_add_f32_e32 v64, 1.0, v64
	v_rcp_f32_e32 v129, v64
	v_exp_f32_e64 v64, -v70
	v_pk_mul_f32 v[126:127], v[126:127], v[128:129]
	s_nop 0
	v_pk_mul_f32 v[120:121], v[120:121], v[126:127]
	v_add_f32_e32 v64, 1.0, v64
	v_cvt_pk_bf16_f32 v126, v120, v121
	v_rcp_f32_e32 v120, v64
	v_exp_f32_e64 v64, -v71
	s_nop 0
	v_add_f32_e32 v64, 1.0, v64
	v_rcp_f32_e32 v121, v64
	s_waitcnt vmcnt(6)
	v_fmamk_f32 v64, v149, 0x3a800000, v244
	v_rsq_f32_e32 v64, v64
	v_pk_mul_f32 v[70:71], v[70:71], v[120:121]
	s_nop 0
	v_pk_mul_f32 v[70:71], v[122:123], v[70:71]
	v_mul_f32_e32 v196, 0x3fb8aa3b, v64
	v_mul_f32_e32 v198, 0x3f317218, v64
	v_pk_mul_f32 v[116:117], v[116:117], v[196:197] op_sel_hi:[1,0]
	v_cvt_pk_bf16_f32 v127, v70, v71
	v_pk_mul_f32 v[70:71], v[118:119], v[196:197] op_sel_hi:[1,0]
	v_exp_f32_e64 v118, -v116
	v_exp_f32_e64 v119, -v117
	v_pk_mul_f32 v[112:113], v[112:113], v[198:199] op_sel_hi:[1,0]
	v_pk_mul_f32 v[114:115], v[114:115], v[198:199] op_sel_hi:[1,0]
	v_add_f32_e32 v118, 1.0, v118
	v_add_f32_e32 v119, 1.0, v119
	v_rcp_f32_e32 v118, v118
	v_rcp_f32_e32 v119, v119
	v_pk_mul_f32 v[108:109], v[108:109], v[196:197] op_sel_hi:[1,0]
	v_pk_mul_f32 v[106:107], v[106:107], v[198:199] op_sel_hi:[1,0]
	v_pk_mul_f32 v[104:105], v[104:105], v[198:199] op_sel_hi:[1,0]
	v_pk_mul_f32 v[116:117], v[116:117], v[118:119]
	global_store_dwordx4 v[66:67], v[124:127], off
	v_pk_mul_f32 v[112:113], v[112:113], v[116:117]
	v_mad_i64_i32 v[66:67], s[10:11], v65, v148, 0
	v_cvt_pk_bf16_f32 v112, v112, v113
	v_exp_f32_e64 v113, -v70
	v_lshl_add_u64 v[66:67], v[66:67], 1, v[68:69]
	v_lshl_add_u64 v[66:67], v[66:67], 0, s[8:9]
	v_lshl_add_u64 v[66:67], v[66:67], 0, s[80:81]
	v_add_f32_e32 v113, 1.0, v113
	v_rcp_f32_e32 v116, v113
	v_exp_f32_e64 v113, -v71
	v_lshl_add_u64 v[66:67], v[66:67], 0, v[214:215]
	v_add_f32_e32 v113, 1.0, v113
	v_rcp_f32_e32 v117, v113
	s_nop 0
	v_pk_mul_f32 v[70:71], v[70:71], v[116:117]
	s_nop 0
	v_pk_mul_f32 v[70:71], v[114:115], v[70:71]
	s_nop 0
	v_cvt_pk_bf16_f32 v113, v70, v71
	v_pk_mul_f32 v[70:71], v[110:111], v[196:197] op_sel_hi:[1,0]
	v_exp_f32_e64 v64, -v108
	s_nop 0
	v_add_f32_e32 v64, 1.0, v64
	v_rcp_f32_e32 v110, v64
	v_exp_f32_e64 v64, -v109
	s_nop 0
	v_add_f32_e32 v64, 1.0, v64
	v_rcp_f32_e32 v111, v64
	v_exp_f32_e64 v64, -v70
	v_pk_mul_f32 v[108:109], v[108:109], v[110:111]
	s_nop 0
	v_pk_mul_f32 v[104:105], v[104:105], v[108:109]
	v_add_f32_e32 v64, 1.0, v64
	v_cvt_pk_bf16_f32 v114, v104, v105
	v_rcp_f32_e32 v104, v64
	v_exp_f32_e64 v64, -v71
	s_nop 0
	v_add_f32_e32 v64, 1.0, v64
	v_rcp_f32_e32 v105, v64
	s_waitcnt vmcnt(6)
; __device__ __forceinline__ unsigned cvtpk(float lo, float hi) { f32x2 v = {lo, hi}; bf16x2_t b = __builtin_convertvector(v, bf16x2_t); return __builtin_bit_cast(unsigned, b); }
; __device__ __forceinline__ float silu_f(float x) { return x * __builtin_amdgcn_rcpf(1.0f + __builtin_amdgcn_exp2f(-LOG2E * x)); }
;     __device__ __forceinline__ void operator()(const pg8::f32x4 (&acc)[2][2][4][2], const pg8::Unit& u, int wr, int wc, int fr, int fq) const {
;     ...
;                 for (int m = 0; m < 4; ++m) rsv[ai][m] = fin[rowb + 128 * ai + 16 * m];
; #pragma unroll
;             for (int ai = 0; ai < 2; ++ai)
; #pragma unroll
;                 for (int m = 0; m < 4; ++m) {
;                     bf16_t* rp = o0 + (size_t)(rowb + 128 * ai + 16 * m) * ldc + u.pn * 128 + wc * 32 + (PERM ? 8 : 4) * fq;
;                     const float rs = __builtin_amdgcn_rsqf(rsv[ai][m] * (1.0f / DM) + EPS);
;                     u32x2 wn[2];
; #pragma unroll
;                     for (int n = 0; n < 2; ++n) {
;                         const pg8::f32x4 g = acc[ai][0][m][n] * rs, up = acc[ai][1][m][n] * rs;
;                         wn[n].x = cvtpk(silu_f(g[0]) * up[0], silu_f(g[1]) * up[1]); wn[n].y = cvtpk(silu_f(g[2]) * up[2], silu_f(g[3]) * up[3]);
;                     }
;                     if (PERM) { *(u32x4*)rp = (u32x4){wn[0].x, wn[0].y, wn[1].x, wn[1].y}; }
;                     else { *(u32x2*)rp = wn[0]; *(u32x2*)(rp + 16) = wn[1]; }
	v_fmamk_f32 v64, v146, 0x3a800000, v244
	v_rsq_f32_e32 v64, v64
	v_pk_mul_f32 v[70:71], v[70:71], v[104:105]
	s_nop 0
	v_pk_mul_f32 v[70:71], v[106:107], v[70:71]
	v_mul_f32_e32 v192, 0x3fb8aa3b, v64
	v_mul_f32_e32 v194, 0x3f317218, v64
	v_pk_mul_f32 v[100:101], v[100:101], v[192:193] op_sel_hi:[1,0]
	v_cvt_pk_bf16_f32 v115, v70, v71
	v_pk_mul_f32 v[70:71], v[102:103], v[192:193] op_sel_hi:[1,0]
	v_exp_f32_e64 v102, -v100
	v_exp_f32_e64 v103, -v101
	v_pk_mul_f32 v[96:97], v[96:97], v[194:195] op_sel_hi:[1,0]
	v_pk_mul_f32 v[98:99], v[98:99], v[194:195] op_sel_hi:[1,0]
	v_add_f32_e32 v102, 1.0, v102
	v_add_f32_e32 v103, 1.0, v103
	v_rcp_f32_e32 v102, v102
	v_rcp_f32_e32 v103, v103
	v_pk_mul_f32 v[92:93], v[92:93], v[192:193] op_sel_hi:[1,0]
	v_pk_mul_f32 v[90:91], v[90:91], v[194:195] op_sel_hi:[1,0]
	v_pk_mul_f32 v[88:89], v[88:89], v[194:195] op_sel_hi:[1,0]
	v_pk_mul_f32 v[100:101], v[100:101], v[102:103]
	global_store_dwordx4 v[66:67], v[112:115], off
	v_pk_mul_f32 v[96:97], v[96:97], v[100:101]
	v_mad_i64_i32 v[66:67], s[10:11], v65, v147, 0
	v_cvt_pk_bf16_f32 v96, v96, v97
	v_exp_f32_e64 v97, -v70
	v_lshl_add_u64 v[66:67], v[66:67], 1, v[68:69]
	v_lshl_add_u64 v[66:67], v[66:67], 0, s[8:9]
	v_lshl_add_u64 v[66:67], v[66:67], 0, s[80:81]
	v_add_f32_e32 v97, 1.0, v97
	v_rcp_f32_e32 v100, v97
	v_exp_f32_e64 v97, -v71
	v_lshl_add_u64 v[66:67], v[66:67], 0, v[214:215]
	v_add_f32_e32 v97, 1.0, v97
	v_rcp_f32_e32 v101, v97
	s_nop 0
	v_pk_mul_f32 v[70:71], v[70:71], v[100:101]
	s_nop 0
	v_pk_mul_f32 v[70:71], v[98:99], v[70:71]
	s_nop 0
	v_cvt_pk_bf16_f32 v97, v70, v71
	v_pk_mul_f32 v[70:71], v[94:95], v[192:193] op_sel_hi:[1,0]
	v_exp_f32_e64 v64, -v92
	s_nop 0
	v_add_f32_e32 v64, 1.0, v64
	v_rcp_f32_e32 v94, v64
	v_exp_f32_e64 v64, -v93
	s_nop 0
	v_add_f32_e32 v64, 1.0, v64
	v_rcp_f32_e32 v95, v64
	v_exp_f32_e64 v64, -v70
	v_pk_mul_f32 v[92:93], v[92:93], v[94:95]
	s_nop 0
	v_pk_mul_f32 v[88:89], v[88:89], v[92:93]
	v_add_f32_e32 v64, 1.0, v64
	v_cvt_pk_bf16_f32 v98, v88, v89
	v_rcp_f32_e32 v88, v64
	v_exp_f32_e64 v64, -v71
	s_nop 0
	v_add_f32_e32 v64, 1.0, v64
	v_rcp_f32_e32 v89, v64
	s_waitcnt vmcnt(6)
	v_fmamk_f32 v64, v144, 0x3a800000, v244
	v_rsq_f32_e32 v64, v64
	v_pk_mul_f32 v[70:71], v[70:71], v[88:89]
	s_nop 0
	v_pk_mul_f32 v[70:71], v[90:91], v[70:71]
	v_mul_f32_e32 v196, 0x3fb8aa3b, v64
	v_mul_f32_e32 v198, 0x3f317218, v64
	v_pk_mul_f32 v[80:81], v[80:81], v[198:199] op_sel_hi:[1,0]
	v_cvt_pk_bf16_f32 v99, v70, v71
	v_pk_mul_f32 v[70:71], v[84:85], v[196:197] op_sel_hi:[1,0]
	v_pk_mul_f32 v[86:87], v[86:87], v[196:197] op_sel_hi:[1,0]
	v_exp_f32_e64 v84, -v70
	v_exp_f32_e64 v85, -v71
	v_pk_mul_f32 v[76:77], v[76:77], v[196:197] op_sel_hi:[1,0]
	v_pk_mul_f32 v[82:83], v[82:83], v[198:199] op_sel_hi:[1,0]
	v_add_f32_e32 v84, 1.0, v84
	v_add_f32_e32 v85, 1.0, v85
	v_rcp_f32_e32 v84, v84
	v_rcp_f32_e32 v85, v85
	v_pk_mul_f32 v[78:79], v[78:79], v[196:197] op_sel_hi:[1,0]
	v_pk_mul_f32 v[74:75], v[74:75], v[198:199] op_sel_hi:[1,0]
	v_pk_mul_f32 v[72:73], v[72:73], v[198:199] op_sel_hi:[1,0]
	v_pk_mul_f32 v[70:71], v[70:71], v[84:85]
	v_pk_mul_f32 v[70:71], v[80:81], v[70:71]
	v_exp_f32_e64 v64, -v76
	v_cvt_pk_bf16_f32 v70, v70, v71
	v_exp_f32_e64 v71, -v86
	v_add_f32_e32 v64, 1.0, v64
	global_store_dwordx4 v[66:67], v[96:99], off
	v_mad_i64_i32 v[66:67], s[10:11], v65, v145, 0
	v_add_f32_e32 v71, 1.0, v71
	v_rcp_f32_e32 v80, v71
	v_exp_f32_e64 v71, -v87
	v_lshl_add_u64 v[66:67], v[66:67], 1, v[68:69]
	v_lshl_add_u64 v[66:67], v[66:67], 0, s[8:9]
	v_lshl_add_u64 v[66:67], v[66:67], 0, s[80:81]
	v_add_f32_e32 v71, 1.0, v71
	v_rcp_f32_e32 v81, v71
	v_lshl_add_u64 v[66:67], v[66:67], 0, v[214:215]
	v_pk_mul_f32 v[80:81], v[86:87], v[80:81]
	s_nop 0
	v_pk_mul_f32 v[80:81], v[82:83], v[80:81]
	s_nop 0
	v_cvt_pk_bf16_f32 v71, v80, v81
	v_rcp_f32_e32 v80, v64
	v_exp_f32_e64 v64, -v77
	s_nop 0
	v_add_f32_e32 v64, 1.0, v64
	v_rcp_f32_e32 v81, v64
	v_exp_f32_e64 v64, -v78
	v_pk_mul_f32 v[76:77], v[76:77], v[80:81]
	s_nop 0
	v_pk_mul_f32 v[72:73], v[72:73], v[76:77]
	v_add_f32_e32 v64, 1.0, v64
	v_rcp_f32_e32 v76, v64
	v_exp_f32_e64 v64, -v79
	v_cvt_pk_bf16_f32 v72, v72, v73
	v_add_f32_e32 v64, 1.0, v64
	v_rcp_f32_e32 v77, v64
	s_waitcnt vmcnt(6)
	v_fmamk_f32 v64, v142, 0x3a800000, v244
	v_rsq_f32_e32 v64, v64
	v_pk_mul_f32 v[76:77], v[78:79], v[76:77]
	s_nop 0
	v_pk_mul_f32 v[74:75], v[74:75], v[76:77]
	v_mul_f32_e32 v192, 0x3fb8aa3b, v64
	v_mul_f32_e32 v194, 0x3f317218, v64
	v_pk_mul_f32 v[60:61], v[60:61], v[192:193] op_sel_hi:[1,0]
	v_cvt_pk_bf16_f32 v73, v74, v75
	global_store_dwordx4 v[66:67], v[70:73], off
	v_pk_mul_f32 v[56:57], v[56:57], v[194:195] op_sel_hi:[1,0]
	v_pk_mul_f32 v[62:63], v[62:63], v[192:193] op_sel_hi:[1,0]
	v_exp_f32_e64 v70, -v60
	v_exp_f32_e64 v71, -v61
	v_pk_mul_f32 v[58:59], v[58:59], v[194:195] op_sel_hi:[1,0]
	v_pk_mul_f32 v[52:53], v[52:53], v[192:193] op_sel_hi:[1,0]
	v_add_f32_e32 v70, 1.0, v70
	v_add_f32_e32 v71, 1.0, v71
	v_rcp_f32_e32 v70, v70
	v_rcp_f32_e32 v71, v71
	v_pk_mul_f32 v[48:49], v[48:49], v[194:195] op_sel_hi:[1,0]
	v_pk_mul_f32 v[54:55], v[54:55], v[192:193] op_sel_hi:[1,0]
	v_pk_mul_f32 v[50:51], v[50:51], v[194:195] op_sel_hi:[1,0]
	v_pk_mul_f32 v[60:61], v[60:61], v[70:71]
	v_mad_i64_i32 v[66:67], s[10:11], v65, v143, 0
	v_pk_mul_f32 v[56:57], v[56:57], v[60:61]
	v_lshl_add_u64 v[66:67], v[66:67], 1, v[68:69]
	v_cvt_pk_bf16_f32 v56, v56, v57
	v_exp_f32_e64 v57, -v62
	v_lshl_add_u64 v[66:67], v[66:67], 0, s[8:9]
	v_lshl_add_u64 v[66:67], v[66:67], 0, s[80:81]
	v_add_f32_e32 v57, 1.0, v57
	v_rcp_f32_e32 v60, v57
	v_exp_f32_e64 v57, -v63
	s_nop 0
	v_add_f32_e32 v57, 1.0, v57
	v_rcp_f32_e32 v61, v57
	s_nop 0
	v_pk_mul_f32 v[60:61], v[62:63], v[60:61]
	s_nop 0
	v_pk_mul_f32 v[58:59], v[58:59], v[60:61]
	s_nop 0
	v_cvt_pk_bf16_f32 v57, v58, v59
	v_exp_f32_e64 v58, -v52
	v_exp_f32_e64 v59, -v53
	v_add_f32_e32 v58, 1.0, v58
	v_add_f32_e32 v59, 1.0, v59
	v_rcp_f32_e32 v58, v58
	v_rcp_f32_e32 v59, v59
	s_nop 0
	v_pk_mul_f32 v[52:53], v[52:53], v[58:59]
	s_nop 0
	v_pk_mul_f32 v[48:49], v[48:49], v[52:53]
	s_nop 0
	v_cvt_pk_bf16_f32 v58, v48, v49
	v_exp_f32_e64 v48, -v54
	v_exp_f32_e64 v49, -v55
	v_add_f32_e32 v48, 1.0, v48
	v_add_f32_e32 v49, 1.0, v49
	v_rcp_f32_e32 v48, v48
	v_rcp_f32_e32 v49, v49
	s_nop 0
	v_pk_mul_f32 v[48:49], v[54:55], v[48:49]
	s_nop 0
	v_pk_mul_f32 v[48:49], v[50:51], v[48:49]
	s_waitcnt vmcnt(6)
; __device__ __forceinline__ unsigned cvtpk(float lo, float hi) { f32x2 v = {lo, hi}; bf16x2_t b = __builtin_convertvector(v, bf16x2_t); return __builtin_bit_cast(unsigned, b); }
; __device__ __forceinline__ float silu_f(float x) { return x * __builtin_amdgcn_rcpf(1.0f + __builtin_amdgcn_exp2f(-LOG2E * x)); }
;     __device__ __forceinline__ void operator()(const pg8::f32x4 (&acc)[2][2][4][2], const pg8::Unit& u, int wr, int wc, int fr, int fq) const {
;     ...
;                 for (int m = 0; m < 4; ++m) rsv[ai][m] = fin[rowb + 128 * ai + 16 * m];
; #pragma unroll
;             for (int ai = 0; ai < 2; ++ai)
; #pragma unroll
;                 for (int m = 0; m < 4; ++m) {
;                     bf16_t* rp = o0 + (size_t)(rowb + 128 * ai + 16 * m) * ldc + u.pn * 128 + wc * 32 + (PERM ? 8 : 4) * fq;
;                     const float rs = __builtin_amdgcn_rsqf(rsv[ai][m] * (1.0f / DM) + EPS);
;                     u32x2 wn[2];
; #pragma unroll
;                     for (int n = 0; n < 2; ++n) {
;                         const pg8::f32x4 g = acc[ai][0][m][n] * rs, up = acc[ai][1][m][n] * rs;
;                         wn[n].x = cvtpk(silu_f(g[0]) * up[0], silu_f(g[1]) * up[1]); wn[n].y = cvtpk(silu_f(g[2]) * up[2], silu_f(g[3]) * up[3]);
;                     }
;                     if (PERM) { *(u32x4*)rp = (u32x4){wn[0].x, wn[0].y, wn[1].x, wn[1].y}; }
;                     else { *(u32x2*)rp = wn[0]; *(u32x2*)(rp + 16) = wn[1]; }
;                 }
	v_fmamk_f32 v50, v140, 0x3a800000, v244
	v_rsq_f32_e32 v50, v50
	v_cvt_pk_bf16_f32 v59, v48, v49
	v_lshl_add_u64 v[48:49], v[66:67], 0, v[214:215]
	global_store_dwordx4 v[48:49], v[56:59], off
	v_mul_f32_e32 v196, 0x3fb8aa3b, v50
	v_mul_f32_e32 v198, 0x3f317218, v50
	v_pk_mul_f32 v[44:45], v[44:45], v[196:197] op_sel_hi:[1,0]
	v_pk_mul_f32 v[46:47], v[46:47], v[196:197] op_sel_hi:[1,0]
	v_pk_mul_f32 v[42:43], v[42:43], v[198:199] op_sel_hi:[1,0]
	v_pk_mul_f32 v[40:41], v[40:41], v[198:199] op_sel_hi:[1,0]
	v_exp_f32_e64 v51, -v44
	v_mad_i64_i32 v[48:49], s[10:11], v65, v141, 0
	v_lshl_add_u64 v[48:49], v[48:49], 1, v[68:69]
	v_add_f32_e32 v51, 1.0, v51
	v_rcp_f32_e32 v52, v51
	v_exp_f32_e64 v51, -v45
	v_lshl_add_u64 v[48:49], v[48:49], 0, s[8:9]
	v_lshl_add_u64 v[48:49], v[48:49], 0, s[80:81]
	v_add_f32_e32 v51, 1.0, v51
	v_rcp_f32_e32 v53, v51
	v_pk_mul_f32 v[36:37], v[36:37], v[196:197] op_sel_hi:[1,0]
	v_pk_mul_f32 v[32:33], v[32:33], v[198:199] op_sel_hi:[1,0]
	v_pk_mul_f32 v[38:39], v[38:39], v[196:197] op_sel_hi:[1,0]
	v_pk_mul_f32 v[44:45], v[44:45], v[52:53]
	v_pk_mul_f32 v[34:35], v[34:35], v[198:199] op_sel_hi:[1,0]
	v_pk_mul_f32 v[40:41], v[40:41], v[44:45]
	s_nop 0
	v_cvt_pk_bf16_f32 v40, v40, v41
	v_exp_f32_e64 v41, -v46
	s_nop 0
	v_add_f32_e32 v41, 1.0, v41
	v_rcp_f32_e32 v44, v41
	v_exp_f32_e64 v41, -v47
	s_nop 0
	v_add_f32_e32 v41, 1.0, v41
	v_rcp_f32_e32 v45, v41
	s_nop 0
	v_pk_mul_f32 v[44:45], v[46:47], v[44:45]
	s_nop 0
	v_pk_mul_f32 v[42:43], v[42:43], v[44:45]
	s_nop 0
	v_cvt_pk_bf16_f32 v41, v42, v43
	v_exp_f32_e64 v42, -v36
	v_exp_f32_e64 v43, -v37
	v_add_f32_e32 v42, 1.0, v42
	v_add_f32_e32 v43, 1.0, v43
	v_rcp_f32_e32 v42, v42
	v_rcp_f32_e32 v43, v43
	s_nop 0
	v_pk_mul_f32 v[36:37], v[36:37], v[42:43]
	s_nop 0
	v_pk_mul_f32 v[32:33], v[32:33], v[36:37]
	s_nop 0
	v_cvt_pk_bf16_f32 v42, v32, v33
	v_exp_f32_e64 v32, -v38
	v_exp_f32_e64 v33, -v39
	v_add_f32_e32 v32, 1.0, v32
	v_add_f32_e32 v33, 1.0, v33
	v_rcp_f32_e32 v32, v32
	v_rcp_f32_e32 v33, v33
	s_nop 0
	v_pk_mul_f32 v[32:33], v[38:39], v[32:33]
	s_nop 0
	v_pk_mul_f32 v[32:33], v[34:35], v[32:33]
	s_waitcnt vmcnt(6)
	v_fmamk_f32 v34, v138, 0x3a800000, v244
	v_rsq_f32_e32 v34, v34
	v_cvt_pk_bf16_f32 v43, v32, v33
	v_lshl_add_u64 v[32:33], v[48:49], 0, v[214:215]
	global_store_dwordx4 v[32:33], v[40:43], off
	v_mul_f32_e32 v192, 0x3fb8aa3b, v34
	v_mul_f32_e32 v194, 0x3f317218, v34
	v_pk_mul_f32 v[28:29], v[28:29], v[192:193] op_sel_hi:[1,0]
	v_pk_mul_f32 v[30:31], v[30:31], v[192:193] op_sel_hi:[1,0]
	v_pk_mul_f32 v[26:27], v[26:27], v[194:195] op_sel_hi:[1,0]
	v_pk_mul_f32 v[24:25], v[24:25], v[194:195] op_sel_hi:[1,0]
	v_exp_f32_e64 v35, -v28
	v_mad_i64_i32 v[32:33], s[10:11], v65, v139, 0
	v_lshl_add_u64 v[32:33], v[32:33], 1, v[68:69]
	v_add_f32_e32 v35, 1.0, v35
	v_rcp_f32_e32 v36, v35
	v_exp_f32_e64 v35, -v29
	v_lshl_add_u64 v[32:33], v[32:33], 0, s[8:9]
	v_lshl_add_u64 v[32:33], v[32:33], 0, s[80:81]
	v_add_f32_e32 v35, 1.0, v35
	v_rcp_f32_e32 v37, v35
	v_pk_mul_f32 v[20:21], v[20:21], v[192:193] op_sel_hi:[1,0]
	v_pk_mul_f32 v[16:17], v[16:17], v[194:195] op_sel_hi:[1,0]
	v_pk_mul_f32 v[22:23], v[22:23], v[192:193] op_sel_hi:[1,0]
	v_pk_mul_f32 v[28:29], v[28:29], v[36:37]
	v_pk_mul_f32 v[18:19], v[18:19], v[194:195] op_sel_hi:[1,0]
	v_pk_mul_f32 v[24:25], v[24:25], v[28:29]
	s_nop 0
	v_cvt_pk_bf16_f32 v24, v24, v25
	v_exp_f32_e64 v25, -v30
	s_nop 0
	v_add_f32_e32 v25, 1.0, v25
	v_rcp_f32_e32 v28, v25
	v_exp_f32_e64 v25, -v31
	s_nop 0
	v_add_f32_e32 v25, 1.0, v25
	v_rcp_f32_e32 v29, v25
	s_nop 0
	v_pk_mul_f32 v[28:29], v[30:31], v[28:29]
	s_nop 0
	v_pk_mul_f32 v[26:27], v[26:27], v[28:29]
	s_nop 0
	v_cvt_pk_bf16_f32 v25, v26, v27
	v_exp_f32_e64 v26, -v20
	v_exp_f32_e64 v27, -v21
	v_add_f32_e32 v26, 1.0, v26
	v_add_f32_e32 v27, 1.0, v27
	v_rcp_f32_e32 v26, v26
	v_rcp_f32_e32 v27, v27
	s_nop 0
	v_pk_mul_f32 v[20:21], v[20:21], v[26:27]
	s_nop 0
	v_pk_mul_f32 v[16:17], v[16:17], v[20:21]
	s_nop 0
	v_cvt_pk_bf16_f32 v26, v16, v17
	v_exp_f32_e64 v16, -v22
	v_exp_f32_e64 v17, -v23
	v_add_f32_e32 v16, 1.0, v16
	v_add_f32_e32 v17, 1.0, v17
	v_rcp_f32_e32 v16, v16
	v_rcp_f32_e32 v17, v17
	s_nop 0
	v_pk_mul_f32 v[16:17], v[22:23], v[16:17]
	s_nop 0
	v_pk_mul_f32 v[16:17], v[18:19], v[16:17]
	s_waitcnt vmcnt(6)
	v_fmamk_f32 v18, v136, 0x3a800000, v244
	v_rsq_f32_e32 v18, v18
	v_cvt_pk_bf16_f32 v27, v16, v17
	v_lshl_add_u64 v[16:17], v[32:33], 0, v[214:215]
	global_store_dwordx4 v[16:17], v[24:27], off
	v_mul_f32_e32 v196, 0x3fb8aa3b, v18
	v_mul_f32_e32 v198, 0x3f317218, v18
	v_pk_mul_f32 v[12:13], v[12:13], v[196:197] op_sel_hi:[1,0]
	v_pk_mul_f32 v[14:15], v[14:15], v[196:197] op_sel_hi:[1,0]
	v_pk_mul_f32 v[10:11], v[10:11], v[198:199] op_sel_hi:[1,0]
	v_pk_mul_f32 v[8:9], v[8:9], v[198:199] op_sel_hi:[1,0]
	v_exp_f32_e64 v19, -v12
	v_mad_i64_i32 v[16:17], s[10:11], v65, v137, 0
	v_lshl_add_u64 v[16:17], v[16:17], 1, v[68:69]
	v_add_f32_e32 v19, 1.0, v19
	v_rcp_f32_e32 v20, v19
	v_exp_f32_e64 v19, -v13
	v_lshl_add_u64 v[16:17], v[16:17], 0, s[8:9]
	v_lshl_add_u64 v[16:17], v[16:17], 0, s[80:81]
	v_add_f32_e32 v19, 1.0, v19
	v_rcp_f32_e32 v21, v19
	v_pk_mul_f32 v[4:5], v[4:5], v[196:197] op_sel_hi:[1,0]
	v_pk_mul_f32 v[0:1], v[0:1], v[198:199] op_sel_hi:[1,0]
	v_pk_mul_f32 v[6:7], v[6:7], v[196:197] op_sel_hi:[1,0]
	v_pk_mul_f32 v[12:13], v[12:13], v[20:21]
	v_pk_mul_f32 v[2:3], v[2:3], v[198:199] op_sel_hi:[1,0]
	v_pk_mul_f32 v[8:9], v[8:9], v[12:13]
	s_nop 0
	v_cvt_pk_bf16_f32 v8, v8, v9
	v_exp_f32_e64 v9, -v14
	s_nop 0
	v_add_f32_e32 v9, 1.0, v9
	v_rcp_f32_e32 v12, v9
	v_exp_f32_e64 v9, -v15
	s_nop 0
	v_add_f32_e32 v9, 1.0, v9
	v_rcp_f32_e32 v13, v9
	s_nop 0
	v_pk_mul_f32 v[12:13], v[14:15], v[12:13]
	s_nop 0
	v_pk_mul_f32 v[10:11], v[10:11], v[12:13]
	s_nop 0
	v_cvt_pk_bf16_f32 v9, v10, v11
	v_exp_f32_e64 v10, -v4
	v_exp_f32_e64 v11, -v5
	v_add_f32_e32 v10, 1.0, v10
	v_add_f32_e32 v11, 1.0, v11
	v_rcp_f32_e32 v10, v10
	v_rcp_f32_e32 v11, v11
	s_nop 0
	v_pk_mul_f32 v[4:5], v[4:5], v[10:11]
	s_nop 0
	v_pk_mul_f32 v[0:1], v[0:1], v[4:5]
	s_nop 0
	v_cvt_pk_bf16_f32 v10, v0, v1
	v_exp_f32_e64 v0, -v6
	v_exp_f32_e64 v1, -v7
	v_add_f32_e32 v0, 1.0, v0
	v_add_f32_e32 v1, 1.0, v1
	v_rcp_f32_e32 v0, v0
	v_rcp_f32_e32 v1, v1
	s_nop 0
	v_pk_mul_f32 v[0:1], v[6:7], v[0:1]
	s_nop 0
	v_pk_mul_f32 v[0:1], v[2:3], v[0:1]
	s_nop 0
	v_cvt_pk_bf16_f32 v11, v0, v1
	v_lshl_add_u64 v[0:1], v[16:17], 0, v[214:215]
	global_store_dwordx4 v[0:1], v[8:11], off
	s_andn2_b64 vcc, exec, s[6:7]
	s_mov_b64 s[6:7], -1
	s_cbranch_vccnz .LBB0_1136
	s_branch .LBB0_1238
